# final fused row-norm: the per-row reloads of the final gain vector (each followed by vmcnt(0) that also drained the row stores) hoisted to one load per vector, waits re-derived
# baseline (speedup 1.0000x reference)
.LBB0_2536:
	s_or_b64 exec, exec, s[30:31]
	s_lshl_b32 s30, s60, 6
	s_ashr_i32 s31, s63, 3
	s_add_i32 s30, s62, s30
	s_and_b32 s31, s31, -8
	s_add_i32 s30, s30, s31
	s_ashr_i32 s31, s30, 31
	s_lshl_b64 s[34:35], s[30:31], 12
	v_lshl_add_u64 v[16:17], v[132:133], 0, s[34:35]
	s_barrier
	global_load_dwordx4 v[100:103], v[134:135], off
	global_load_dwordx4 v[104:107], v[134:135], off offset:1024
	global_load_dwordx4 v[108:111], v[134:135], off offset:2048
	global_load_dwordx4 v[112:115], v[134:135], off offset:3072
	global_load_dwordx4 v[18:21], v[16:17], off
	global_load_dwordx4 v[30:33], v[16:17], off offset:1024
	global_load_dwordx4 v[34:37], v[16:17], off offset:3072
	global_load_dwordx4 v[38:41], v[16:17], off offset:2048
	s_or_b32 s34, s30, 1
	s_ashr_i32 s35, s34, 31
	s_lshl_b64 s[34:35], s[34:35], 12
	v_lshl_add_u64 v[28:29], v[132:133], 0, s[34:35]
	global_load_dwordx4 v[8:11], v[28:29], off
	global_load_dwordx4 v[0:3], v[28:29], off offset:1024
	global_load_dwordx4 v[4:7], v[28:29], off offset:3072
	global_load_dwordx4 v[12:15], v[28:29], off offset:2048
	s_or_b32 s34, s30, 2
	s_ashr_i32 s35, s34, 31
	s_lshl_b64 s[34:35], s[34:35], 12
	s_waitcnt vmcnt(7)
	v_pk_mul_f32 v[22:23], v[20:21], v[20:21]
	v_pk_mul_f32 v[24:25], v[18:19], v[18:19]
	s_waitcnt vmcnt(6)
	v_pk_mul_f32 v[26:27], v[32:33], v[32:33]
	v_pk_mul_f32 v[46:47], v[30:31], v[30:31]
	s_waitcnt vmcnt(4)
	v_mul_f32_e32 v48, v39, v39
	v_mul_f32_e32 v50, v41, v41
	v_mul_f32_e32 v64, v36, v36
	v_mul_f32_e32 v65, v37, v37
	v_pk_mov_b32 v[52:53], v[24:25], v[22:23] op_sel:[1, 0]
	v_mov_b32_e32 v25, v23
	v_pk_mov_b32 v[22:23], v[46:47], v[26:27] op_sel:[1, 0]
	v_mov_b32_e32 v47, v27
	v_pk_fma_f32 v[26:27], v[38:39], v[38:39], v[48:49] op_sel_hi:[1, 1, 0]
	v_pk_fma_f32 v[48:49], v[40:41], v[40:41], v[50:51] op_sel_hi:[1, 1, 0]
	s_waitcnt vmcnt(3)
	v_pk_mul_f32 v[50:51], v[10:11], v[10:11]
	v_pk_mul_f32 v[54:55], v[8:9], v[8:9]
	s_waitcnt vmcnt(2)
	v_pk_mul_f32 v[56:57], v[2:3], v[2:3]
	v_pk_mul_f32 v[58:59], v[0:1], v[0:1]
	v_pk_add_f32 v[22:23], v[22:23], v[46:47]
	v_mov_b32_e32 v27, v64
	v_mov_b32_e32 v49, v65
	v_pk_mov_b32 v[46:47], v[54:55], v[50:51] op_sel:[1, 0]
	v_mov_b32_e32 v55, v51
	v_pk_mov_b32 v[50:51], v[58:59], v[56:57] op_sel:[1, 0]
	v_mov_b32_e32 v59, v57
	v_mul_f32_e32 v61, v34, v34
	v_mul_f32_e32 v63, v35, v35
	s_waitcnt vmcnt(0)
	v_mul_f32_e32 v60, v13, v13
	v_mul_f32_e32 v62, v15, v15
	v_pk_add_f32 v[24:25], v[52:53], v[24:25]
	v_pk_add_f32 v[26:27], v[26:27], v[48:49]
	v_pk_add_f32 v[46:47], v[46:47], v[54:55]
	v_pk_add_f32 v[48:49], v[50:51], v[58:59]
	v_mul_f32_e32 v66, v4, v4
	v_mul_f32_e32 v67, v5, v5
	v_mul_f32_e32 v68, v6, v6
	v_mul_f32_e32 v69, v7, v7
	v_pk_fma_f32 v[52:53], v[12:13], v[12:13], v[60:61] op_sel_hi:[1, 1, 0]
	v_pk_fma_f32 v[56:57], v[14:15], v[14:15], v[62:63] op_sel_hi:[1, 1, 0]
	v_pk_add_f32 v[24:25], v[24:25], v[24:25] op_sel:[0, 1] op_sel_hi:[1, 0]
	v_pk_add_f32 v[22:23], v[22:23], v[22:23] op_sel:[0, 1] op_sel_hi:[1, 0]
	v_pk_add_f32 v[46:47], v[46:47], v[46:47] op_sel:[0, 1] op_sel_hi:[1, 0]
	v_pk_add_f32 v[48:49], v[48:49], v[48:49] op_sel:[0, 1] op_sel_hi:[1, 0]
	v_mov_b32_e32 v53, v68
	v_mov_b32_e32 v57, v69
	v_mov_b32_e32 v25, v61
	v_mov_b32_e32 v23, v63
	v_mov_b32_e32 v47, v66
	v_mov_b32_e32 v49, v67
	v_pk_add_f32 v[50:51], v[52:53], v[56:57]
	v_pk_add_f32 v[22:23], v[24:25], v[22:23]
	v_pk_add_f32 v[24:25], v[46:47], v[48:49]
	v_pk_add_f32 v[22:23], v[22:23], v[26:27]
	v_pk_add_f32 v[24:25], v[24:25], v[50:51]
	v_mov_b32_e32 v27, v22
	v_mov_b32_e32 v26, v24
	v_mov_b32_e32 v22, v25
	v_pk_add_f32 v[22:23], v[26:27], v[22:23]
	v_lshl_add_u64 v[52:53], v[132:133], 0, s[34:35]
	s_or_b32 s34, s30, 3
	s_ashr_i32 s35, s34, 31
	s_lshl_b64 s[34:35], s[34:35], 12
	s_waitcnt lgkmcnt(0)
	s_nop 1
	v_add_f32_dpp v22, v22, v22 quad_perm:[1, 0, 3, 2] row_mask:0xf bank_mask:0xf
	v_add_f32_dpp v23, v23, v23 quad_perm:[1, 0, 3, 2] row_mask:0xf bank_mask:0xf
	s_waitcnt lgkmcnt(0)
	s_nop 1
	v_add_f32_dpp v22, v22, v22 quad_perm:[2, 3, 0, 1] row_mask:0xf bank_mask:0xf
	v_add_f32_dpp v23, v23, v23 quad_perm:[2, 3, 0, 1] row_mask:0xf bank_mask:0xf
	s_waitcnt lgkmcnt(0)
	s_nop 1
	v_add_f32_dpp v22, v22, v22 row_half_mirror row_mask:0xf bank_mask:0xf
	v_add_f32_dpp v23, v23, v23 row_half_mirror row_mask:0xf bank_mask:0xf
	s_waitcnt lgkmcnt(0)
	s_nop 1
	v_add_f32_dpp v22, v22, v22 row_mirror row_mask:0xf bank_mask:0xf
	v_add_f32_dpp v23, v23, v23 row_mirror row_mask:0xf bank_mask:0xf
	ds_bpermute_b32 v25, v175, v23
	ds_bpermute_b32 v24, v175, v22
	s_waitcnt lgkmcnt(0)
	v_pk_add_f32 v[22:23], v[22:23], v[24:25]
	v_mov_b64_e32 v[24:25], s[26:27]
	s_waitcnt lgkmcnt(0)
	v_mov_b32_e32 v26, v22
	v_mov_b32_e32 v27, v23
	s_nop 1
	v_permlane32_swap_b32_e32 v26, v22
	v_permlane32_swap_b32_e32 v27, v23
	v_pk_add_f32 v[22:23], v[22:23], v[26:27]
	s_nop 0
	v_pk_fma_f32 v[22:23], v[22:23], s[24:25], v[24:25] op_sel_hi:[1, 0, 0]
	s_nop 0
	v_mul_f32_e32 v26, 0x4b800000, v23
	v_cmp_gt_f32_e32 vcc, s57, v23
	s_nop 1
	v_cndmask_b32_e32 v23, v23, v26, vcc
	v_rsq_f32_e32 v23, v23
	s_nop 0
	v_mul_f32_e32 v26, 0x45800000, v23
	v_cndmask_b32_e32 v26, v23, v26, vcc
	v_pk_mul_f32 v[18:19], v[18:19], v[26:27] op_sel_hi:[1, 0]
	v_pk_mul_f32 v[20:21], v[20:21], v[26:27] op_sel_hi:[1, 0]
	v_pk_mul_f32 v[18:19], v[100:101], v[18:19]
	v_pk_mul_f32 v[20:21], v[102:103], v[20:21]
	global_store_dwordx4 v[16:17], v[18:21], off
	v_pk_mul_f32 v[32:33], v[32:33], v[26:27] op_sel_hi:[1, 0]
	v_pk_mul_f32 v[30:31], v[30:31], v[26:27] op_sel_hi:[1, 0]
	v_cmp_gt_f32_e32 vcc, s57, v22
	v_pk_mul_f32 v[18:19], v[104:105], v[30:31]
	v_pk_mul_f32 v[20:21], v[106:107], v[32:33]
	global_store_dwordx4 v[16:17], v[18:21], off offset:1024
	v_pk_mul_f32 v[30:31], v[40:41], v[26:27] op_sel_hi:[1, 0]
	v_pk_mul_f32 v[32:33], v[38:39], v[26:27] op_sel_hi:[1, 0]
	s_nop 1
	v_pk_mul_f32 v[20:21], v[110:111], v[30:31]
	v_pk_mul_f32 v[18:19], v[108:109], v[32:33]
	global_store_dwordx4 v[16:17], v[18:21], off offset:2048
	v_pk_mul_f32 v[30:31], v[36:37], v[26:27] op_sel_hi:[1, 0]
	v_pk_mul_f32 v[26:27], v[34:35], v[26:27] op_sel_hi:[1, 0]
	s_nop 1
	v_pk_mul_f32 v[20:21], v[114:115], v[30:31]
	v_pk_mul_f32 v[18:19], v[112:113], v[26:27]
	global_store_dwordx4 v[16:17], v[18:21], off offset:3072
	v_lshl_add_u64 v[26:27], v[132:133], 0, s[34:35]
	s_nop 1
	v_mul_f32_e32 v20, 0x4b800000, v22
	s_nop 1
	v_cndmask_b32_e32 v20, v22, v20, vcc
	v_rsq_f32_e32 v20, v20
	s_or_b32 s34, s30, 4
	s_ashr_i32 s35, s34, 31
	s_lshl_b64 s[34:35], s[34:35], 12
	v_mul_f32_e32 v21, 0x45800000, v20
	v_cndmask_b32_e32 v50, v20, v21, vcc
	v_pk_mul_f32 v[10:11], v[10:11], v[50:51] op_sel_hi:[1, 0]
	v_pk_mul_f32 v[8:9], v[8:9], v[50:51] op_sel_hi:[1, 0]
	v_pk_mul_f32 v[2:3], v[2:3], v[50:51] op_sel_hi:[1, 0]
	v_pk_mul_f32 v[0:1], v[0:1], v[50:51] op_sel_hi:[1, 0]
	v_pk_mul_f32 v[14:15], v[14:15], v[50:51] op_sel_hi:[1, 0]
	v_pk_mul_f32 v[12:13], v[12:13], v[50:51] op_sel_hi:[1, 0]
	v_pk_mul_f32 v[8:9], v[100:101], v[8:9]
	v_pk_mul_f32 v[10:11], v[102:103], v[10:11]
	global_store_dwordx4 v[28:29], v[8:11], off
	v_pk_mul_f32 v[0:1], v[104:105], v[0:1]
	v_pk_mul_f32 v[2:3], v[106:107], v[2:3]
	global_store_dwordx4 v[28:29], v[0:3], off offset:1024
	global_load_dwordx4 v[34:37], v[52:53], off
	global_load_dwordx4 v[38:41], v[52:53], off offset:1024
	global_load_dwordx4 v[42:45], v[52:53], off offset:3072
	global_load_dwordx4 v[46:49], v[52:53], off offset:2048
	global_load_dwordx4 v[20:23], v[26:27], off
	global_load_dwordx4 v[16:19], v[26:27], off offset:1024
	global_load_dwordx4 v[0:3], v[26:27], off offset:3072
	global_load_dwordx4 v[8:11], v[26:27], off offset:2048
	s_waitcnt vmcnt(3)
	v_pk_mul_f32 v[62:63], v[22:23], v[22:23]
	v_pk_mul_f32 v[12:13], v[108:109], v[12:13]
	v_pk_mul_f32 v[14:15], v[110:111], v[14:15]
	global_store_dwordx4 v[28:29], v[12:15], off offset:2048
	v_mul_f32_e32 v51, v44, v44
	v_pk_mul_f32 v[6:7], v[6:7], v[50:51] op_sel_hi:[1, 0]
	v_pk_mul_f32 v[4:5], v[4:5], v[50:51] op_sel_hi:[1, 0]
	v_pk_mul_f32 v[30:31], v[36:37], v[36:37]
	v_pk_mul_f32 v[32:33], v[34:35], v[34:35]
	v_pk_mul_f32 v[54:55], v[40:41], v[40:41]
	v_pk_mul_f32 v[56:57], v[38:39], v[38:39]
	v_mul_f32_e32 v58, v47, v47
	v_mul_f32_e32 v60, v49, v49
	v_pk_mul_f32 v[64:65], v[20:21], v[20:21]
	s_waitcnt vmcnt(3)
	v_pk_mul_f32 v[66:67], v[18:19], v[18:19]
	v_pk_mul_f32 v[68:69], v[16:17], v[16:17]
	v_pk_mov_b32 v[74:75], v[32:33], v[30:31] op_sel:[1, 0]
	v_mov_b32_e32 v33, v31
	v_pk_mov_b32 v[30:31], v[56:57], v[54:55] op_sel:[1, 0]
	v_mov_b32_e32 v57, v55
	v_pk_fma_f32 v[54:55], v[46:47], v[46:47], v[58:59] op_sel_hi:[1, 1, 0]
	v_pk_fma_f32 v[58:59], v[48:49], v[48:49], v[60:61] op_sel_hi:[1, 1, 0]
	v_pk_mov_b32 v[60:61], v[64:65], v[62:63] op_sel:[1, 0]
	v_mov_b32_e32 v65, v63
	v_pk_mov_b32 v[62:63], v[68:69], v[66:67] op_sel:[1, 0]
	v_mov_b32_e32 v69, v67
	v_mul_f32_e32 v73, v42, v42
	s_waitcnt vmcnt(1)
	v_mul_f32_e32 v70, v9, v9
	v_mul_f32_e32 v72, v11, v11
	v_pk_add_f32 v[32:33], v[74:75], v[32:33]
	v_mul_f32_e32 v76, v43, v43
	v_mul_f32_e32 v77, v45, v45
	v_mul_f32_e32 v78, v0, v0
	v_mul_f32_e32 v79, v1, v1
	v_mul_f32_e32 v80, v2, v2
	v_mul_f32_e32 v81, v3, v3
	v_pk_fma_f32 v[66:67], v[8:9], v[8:9], v[70:71] op_sel_hi:[1, 1, 0]
	v_pk_fma_f32 v[70:71], v[10:11], v[10:11], v[72:73] op_sel_hi:[1, 1, 0]
	v_mov_b32_e32 v55, v51
	v_mov_b32_e32 v59, v77
	v_mov_b32_e32 v67, v80
	v_mov_b32_e32 v71, v81
	v_pk_add_f32 v[50:51], v[66:67], v[70:71]
	v_pk_mul_f32 v[4:5], v[112:113], v[4:5]
	v_pk_mul_f32 v[6:7], v[114:115], v[6:7]
	global_store_dwordx4 v[28:29], v[4:7], off offset:3072
	v_pk_add_f32 v[12:13], v[30:31], v[56:57]
	v_pk_add_f32 v[14:15], v[60:61], v[64:65]
	v_pk_add_f32 v[28:29], v[62:63], v[68:69]
	v_pk_add_f32 v[30:31], v[32:33], v[32:33] op_sel:[0, 1] op_sel_hi:[1, 0]
	v_pk_add_f32 v[12:13], v[12:13], v[12:13] op_sel:[0, 1] op_sel_hi:[1, 0]
	v_pk_add_f32 v[14:15], v[14:15], v[14:15] op_sel:[0, 1] op_sel_hi:[1, 0]
	v_pk_add_f32 v[28:29], v[28:29], v[28:29] op_sel:[0, 1] op_sel_hi:[1, 0]
	v_mov_b32_e32 v31, v73
	v_mov_b32_e32 v13, v76
	v_mov_b32_e32 v15, v78
	v_mov_b32_e32 v29, v79
	v_pk_add_f32 v[32:33], v[54:55], v[58:59]
	v_pk_add_f32 v[12:13], v[30:31], v[12:13]
	v_pk_add_f32 v[14:15], v[14:15], v[28:29]
	v_pk_add_f32 v[12:13], v[12:13], v[32:33]
	v_pk_add_f32 v[14:15], v[14:15], v[50:51]
	v_mov_b32_e32 v29, v12
	v_mov_b32_e32 v28, v14
	v_mov_b32_e32 v12, v15
	v_pk_add_f32 v[12:13], v[28:29], v[12:13]
	s_waitcnt lgkmcnt(0)
	s_nop 1
	v_add_f32_dpp v12, v12, v12 quad_perm:[1, 0, 3, 2] row_mask:0xf bank_mask:0xf
	v_add_f32_dpp v13, v13, v13 quad_perm:[1, 0, 3, 2] row_mask:0xf bank_mask:0xf
	s_waitcnt lgkmcnt(0)
	s_nop 1
	v_add_f32_dpp v12, v12, v12 quad_perm:[2, 3, 0, 1] row_mask:0xf bank_mask:0xf
	v_add_f32_dpp v13, v13, v13 quad_perm:[2, 3, 0, 1] row_mask:0xf bank_mask:0xf
	s_waitcnt lgkmcnt(0)
	s_nop 1
	v_add_f32_dpp v12, v12, v12 row_half_mirror row_mask:0xf bank_mask:0xf
	v_add_f32_dpp v13, v13, v13 row_half_mirror row_mask:0xf bank_mask:0xf
	s_waitcnt lgkmcnt(0)
	s_nop 1
	v_add_f32_dpp v12, v12, v12 row_mirror row_mask:0xf bank_mask:0xf
	v_add_f32_dpp v13, v13, v13 row_mirror row_mask:0xf bank_mask:0xf
	ds_bpermute_b32 v15, v175, v13
	ds_bpermute_b32 v14, v175, v12
	s_waitcnt lgkmcnt(0)
	v_pk_add_f32 v[12:13], v[12:13], v[14:15]
	s_waitcnt lgkmcnt(0)
	v_mov_b32_e32 v14, v12
	v_mov_b32_e32 v15, v13
	s_nop 1
	v_permlane32_swap_b32_e32 v14, v12
	v_permlane32_swap_b32_e32 v15, v13
	v_pk_add_f32 v[12:13], v[12:13], v[14:15]
	s_nop 0
	v_pk_fma_f32 v[12:13], v[12:13], s[24:25], v[24:25] op_sel_hi:[1, 0, 0]
	s_nop 0
	v_mul_f32_e32 v14, 0x4b800000, v13
	v_cmp_gt_f32_e32 vcc, s57, v13
	s_nop 1
	v_cndmask_b32_e32 v13, v13, v14, vcc
	v_rsq_f32_e32 v13, v13
	s_nop 0
	v_mul_f32_e32 v14, 0x45800000, v13
	v_cndmask_b32_e32 v14, v13, v14, vcc
	v_pk_mul_f32 v[28:29], v[36:37], v[14:15] op_sel_hi:[1, 0]
	v_pk_mul_f32 v[30:31], v[34:35], v[14:15] op_sel_hi:[1, 0]
	v_mul_f32_e32 v13, 0x4b800000, v12
	v_cmp_gt_f32_e32 vcc, s57, v12
	v_pk_mul_f32 v[4:5], v[100:101], v[30:31]
	v_pk_mul_f32 v[6:7], v[102:103], v[28:29]
	global_store_dwordx4 v[52:53], v[4:7], off
	v_pk_mul_f32 v[28:29], v[40:41], v[14:15] op_sel_hi:[1, 0]
	v_pk_mul_f32 v[30:31], v[38:39], v[14:15] op_sel_hi:[1, 0]
	v_cndmask_b32_e32 v12, v12, v13, vcc
	v_rsq_f32_e32 v12, v12
	v_pk_mul_f32 v[4:5], v[104:105], v[30:31]
	v_pk_mul_f32 v[6:7], v[106:107], v[28:29]
	global_store_dwordx4 v[52:53], v[4:7], off offset:1024
	v_pk_mul_f32 v[28:29], v[48:49], v[14:15] op_sel_hi:[1, 0]
	v_pk_mul_f32 v[30:31], v[46:47], v[14:15] op_sel_hi:[1, 0]
	v_mul_f32_e32 v13, 0x45800000, v12
	v_pk_mul_f32 v[4:5], v[108:109], v[30:31]
	v_pk_mul_f32 v[6:7], v[110:111], v[28:29]
	global_store_dwordx4 v[52:53], v[4:7], off offset:2048
	v_pk_mul_f32 v[28:29], v[44:45], v[14:15] op_sel_hi:[1, 0]
	v_pk_mul_f32 v[14:15], v[42:43], v[14:15] op_sel_hi:[1, 0]
	v_lshl_add_u64 v[30:31], v[132:133], 0, s[34:35]
	s_or_b32 s34, s30, 5
	s_ashr_i32 s35, s34, 31
	s_lshl_b64 s[34:35], s[34:35], 12
	v_pk_mul_f32 v[4:5], v[112:113], v[14:15]
	v_pk_mul_f32 v[6:7], v[114:115], v[28:29]
	global_store_dwordx4 v[52:53], v[4:7], off offset:3072
	v_cndmask_b32_e32 v52, v12, v13, vcc
	v_pk_mul_f32 v[12:13], v[22:23], v[52:53] op_sel_hi:[1, 0]
	v_pk_mul_f32 v[14:15], v[20:21], v[52:53] op_sel_hi:[1, 0]
	v_pk_mul_f32 v[10:11], v[10:11], v[52:53] op_sel_hi:[1, 0]
	v_pk_mul_f32 v[8:9], v[8:9], v[52:53] op_sel_hi:[1, 0]
	v_lshl_add_u64 v[28:29], v[132:133], 0, s[34:35]
	s_or_b32 s34, s30, 6
	s_or_b32 s30, s30, 7
	s_ashr_i32 s35, s34, 31
	s_ashr_i32 s31, s30, 31
	s_lshl_b64 s[34:35], s[34:35], 12
	s_lshl_b64 s[30:31], s[30:31], 12
	v_pk_mul_f32 v[4:5], v[100:101], v[14:15]
	v_pk_mul_f32 v[6:7], v[102:103], v[12:13]
	global_store_dwordx4 v[26:27], v[4:7], off
	v_pk_mul_f32 v[12:13], v[18:19], v[52:53] op_sel_hi:[1, 0]
	v_pk_mul_f32 v[14:15], v[16:17], v[52:53] op_sel_hi:[1, 0]
	s_nop 1
	v_pk_mul_f32 v[6:7], v[106:107], v[12:13]
	v_pk_mul_f32 v[4:5], v[104:105], v[14:15]
	global_store_dwordx4 v[26:27], v[4:7], off offset:1024
	global_load_dwordx4 v[36:39], v[30:31], off
	global_load_dwordx4 v[40:43], v[30:31], off offset:1024
	global_load_dwordx4 v[44:47], v[30:31], off offset:3072
	global_load_dwordx4 v[48:51], v[30:31], off offset:2048
	global_load_dwordx4 v[20:23], v[28:29], off
	global_load_dwordx4 v[16:19], v[28:29], off offset:1024
	global_load_dwordx4 v[4:7], v[28:29], off offset:3072
	global_load_dwordx4 v[12:15], v[28:29], off offset:2048
	s_waitcnt vmcnt(6)
	v_pk_mul_f32 v[54:55], v[42:43], v[42:43]
	v_pk_mul_f32 v[8:9], v[108:109], v[8:9]
	v_pk_mul_f32 v[10:11], v[110:111], v[10:11]
	global_store_dwordx4 v[26:27], v[8:11], off offset:2048
	s_waitcnt vmcnt(6)
	v_mul_f32_e32 v53, v46, v46
	v_pk_mul_f32 v[2:3], v[2:3], v[52:53] op_sel_hi:[1, 0]
	v_pk_mul_f32 v[0:1], v[0:1], v[52:53] op_sel_hi:[1, 0]
	v_pk_mul_f32 v[32:33], v[38:39], v[38:39]
	v_pk_mul_f32 v[34:35], v[36:37], v[36:37]
	v_pk_mul_f32 v[56:57], v[40:41], v[40:41]
	s_waitcnt vmcnt(5)
	v_mul_f32_e32 v58, v49, v49
	v_mul_f32_e32 v60, v51, v51
	s_waitcnt vmcnt(4)
	v_pk_mul_f32 v[62:63], v[22:23], v[22:23]
	v_pk_mul_f32 v[64:65], v[20:21], v[20:21]
	s_waitcnt vmcnt(3)
	v_pk_mul_f32 v[66:67], v[18:19], v[18:19]
	v_pk_mul_f32 v[68:69], v[16:17], v[16:17]
	v_pk_mov_b32 v[74:75], v[34:35], v[32:33] op_sel:[1, 0]
	v_mov_b32_e32 v35, v33
	v_pk_mov_b32 v[32:33], v[56:57], v[54:55] op_sel:[1, 0]
	v_mov_b32_e32 v57, v55
	v_pk_fma_f32 v[54:55], v[48:49], v[48:49], v[58:59] op_sel_hi:[1, 1, 0]
	v_pk_fma_f32 v[58:59], v[50:51], v[50:51], v[60:61] op_sel_hi:[1, 1, 0]
	v_pk_mov_b32 v[60:61], v[64:65], v[62:63] op_sel:[1, 0]
	v_mov_b32_e32 v65, v63
	v_pk_mov_b32 v[62:63], v[68:69], v[66:67] op_sel:[1, 0]
	v_mov_b32_e32 v69, v67
	v_mul_f32_e32 v73, v44, v44
	s_waitcnt vmcnt(1)
	v_mul_f32_e32 v70, v13, v13
	v_mul_f32_e32 v72, v15, v15
	v_pk_add_f32 v[34:35], v[74:75], v[34:35]
	v_mul_f32_e32 v76, v45, v45
	v_mul_f32_e32 v77, v47, v47
	v_mul_f32_e32 v78, v4, v4
	v_mul_f32_e32 v79, v5, v5
	v_mul_f32_e32 v80, v6, v6
	v_mul_f32_e32 v81, v7, v7
	v_pk_fma_f32 v[66:67], v[12:13], v[12:13], v[70:71] op_sel_hi:[1, 1, 0]
	v_pk_fma_f32 v[70:71], v[14:15], v[14:15], v[72:73] op_sel_hi:[1, 1, 0]
	v_mov_b32_e32 v55, v53
	v_mov_b32_e32 v59, v77
	v_mov_b32_e32 v67, v80
	v_mov_b32_e32 v71, v81
	v_pk_add_f32 v[52:53], v[66:67], v[70:71]
	v_pk_mul_f32 v[0:1], v[112:113], v[0:1]
	v_pk_mul_f32 v[2:3], v[114:115], v[2:3]
	global_store_dwordx4 v[26:27], v[0:3], off offset:3072
	v_pk_add_f32 v[8:9], v[32:33], v[56:57]
	v_pk_add_f32 v[10:11], v[60:61], v[64:65]
	v_pk_add_f32 v[26:27], v[62:63], v[68:69]
	v_pk_add_f32 v[32:33], v[34:35], v[34:35] op_sel:[0, 1] op_sel_hi:[1, 0]
	v_pk_add_f32 v[8:9], v[8:9], v[8:9] op_sel:[0, 1] op_sel_hi:[1, 0]
	v_pk_add_f32 v[10:11], v[10:11], v[10:11] op_sel:[0, 1] op_sel_hi:[1, 0]
	v_pk_add_f32 v[26:27], v[26:27], v[26:27] op_sel:[0, 1] op_sel_hi:[1, 0]
	v_mov_b32_e32 v33, v73
	v_mov_b32_e32 v9, v76
	v_mov_b32_e32 v11, v78
	v_mov_b32_e32 v27, v79
	v_pk_add_f32 v[34:35], v[54:55], v[58:59]
	v_pk_add_f32 v[8:9], v[32:33], v[8:9]
	v_pk_add_f32 v[10:11], v[10:11], v[26:27]
	v_pk_add_f32 v[8:9], v[8:9], v[34:35]
	v_pk_add_f32 v[10:11], v[10:11], v[52:53]
	v_mov_b32_e32 v27, v8
	v_mov_b32_e32 v26, v10
	v_mov_b32_e32 v8, v11
	v_pk_add_f32 v[8:9], v[26:27], v[8:9]
	v_lshl_add_u64 v[52:53], v[132:133], 0, s[34:35]
	s_waitcnt lgkmcnt(0)
	s_nop 1
	v_add_f32_dpp v8, v8, v8 quad_perm:[1, 0, 3, 2] row_mask:0xf bank_mask:0xf
	v_add_f32_dpp v9, v9, v9 quad_perm:[1, 0, 3, 2] row_mask:0xf bank_mask:0xf
	s_waitcnt lgkmcnt(0)
	s_nop 1
	v_add_f32_dpp v8, v8, v8 quad_perm:[2, 3, 0, 1] row_mask:0xf bank_mask:0xf
	v_add_f32_dpp v9, v9, v9 quad_perm:[2, 3, 0, 1] row_mask:0xf bank_mask:0xf
	s_waitcnt lgkmcnt(0)
	s_nop 1
	v_add_f32_dpp v8, v8, v8 row_half_mirror row_mask:0xf bank_mask:0xf
	v_add_f32_dpp v9, v9, v9 row_half_mirror row_mask:0xf bank_mask:0xf
	s_waitcnt lgkmcnt(0)
	s_nop 1
	v_add_f32_dpp v8, v8, v8 row_mirror row_mask:0xf bank_mask:0xf
	v_add_f32_dpp v9, v9, v9 row_mirror row_mask:0xf bank_mask:0xf
	ds_bpermute_b32 v11, v175, v9
	ds_bpermute_b32 v10, v175, v8
	s_waitcnt lgkmcnt(0)
	v_pk_add_f32 v[8:9], v[8:9], v[10:11]
	s_waitcnt lgkmcnt(0)
	v_mov_b32_e32 v10, v8
	v_mov_b32_e32 v11, v9
	s_nop 1
	v_permlane32_swap_b32_e32 v10, v8
	v_permlane32_swap_b32_e32 v11, v9
	v_pk_add_f32 v[8:9], v[8:9], v[10:11]
	s_nop 0
	v_pk_fma_f32 v[8:9], v[8:9], s[24:25], v[24:25] op_sel_hi:[1, 0, 0]
	s_nop 0
	v_mul_f32_e32 v10, 0x4b800000, v9
	v_cmp_gt_f32_e32 vcc, s57, v9
	s_nop 1
	v_cndmask_b32_e32 v9, v9, v10, vcc
	v_rsq_f32_e32 v9, v9
	s_nop 0
	v_mul_f32_e32 v10, 0x45800000, v9
	v_cndmask_b32_e32 v10, v9, v10, vcc
	v_pk_mul_f32 v[26:27], v[36:37], v[10:11] op_sel_hi:[1, 0]
	v_pk_mul_f32 v[32:33], v[38:39], v[10:11] op_sel_hi:[1, 0]
	v_mul_f32_e32 v9, 0x4b800000, v8
	v_cmp_gt_f32_e32 vcc, s57, v8
	v_pk_mul_f32 v[2:3], v[102:103], v[32:33]
	v_pk_mul_f32 v[0:1], v[100:101], v[26:27]
	global_store_dwordx4 v[30:31], v[0:3], off
	v_pk_mul_f32 v[26:27], v[42:43], v[10:11] op_sel_hi:[1, 0]
	v_pk_mul_f32 v[32:33], v[40:41], v[10:11] op_sel_hi:[1, 0]
	v_cndmask_b32_e32 v8, v8, v9, vcc
	v_rsq_f32_e32 v8, v8
	v_pk_mul_f32 v[0:1], v[104:105], v[32:33]
	v_pk_mul_f32 v[2:3], v[106:107], v[26:27]
	global_store_dwordx4 v[30:31], v[0:3], off offset:1024
	v_pk_mul_f32 v[26:27], v[50:51], v[10:11] op_sel_hi:[1, 0]
	v_pk_mul_f32 v[32:33], v[48:49], v[10:11] op_sel_hi:[1, 0]
	v_mul_f32_e32 v9, 0x45800000, v8
	v_cndmask_b32_e32 v50, v8, v9, vcc
	v_pk_mul_f32 v[8:9], v[22:23], v[50:51] op_sel_hi:[1, 0]
	v_pk_mul_f32 v[14:15], v[14:15], v[50:51] op_sel_hi:[1, 0]
	v_pk_mul_f32 v[12:13], v[12:13], v[50:51] op_sel_hi:[1, 0]
	v_pk_mul_f32 v[0:1], v[108:109], v[32:33]
	v_pk_mul_f32 v[2:3], v[110:111], v[26:27]
	global_store_dwordx4 v[30:31], v[0:3], off offset:2048
	v_pk_mul_f32 v[26:27], v[46:47], v[10:11] op_sel_hi:[1, 0]
	v_pk_mul_f32 v[10:11], v[44:45], v[10:11] op_sel_hi:[1, 0]
	s_nop 1
	v_pk_mul_f32 v[2:3], v[114:115], v[26:27]
	v_pk_mul_f32 v[0:1], v[112:113], v[10:11]
	global_store_dwordx4 v[30:31], v[0:3], off offset:3072
	v_pk_mul_f32 v[10:11], v[20:21], v[50:51] op_sel_hi:[1, 0]
	v_lshl_add_u64 v[26:27], v[132:133], 0, s[30:31]
	s_nop 1
	v_pk_mul_f32 v[0:1], v[100:101], v[10:11]
	v_pk_mul_f32 v[2:3], v[102:103], v[8:9]
	global_store_dwordx4 v[28:29], v[0:3], off
	v_pk_mul_f32 v[8:9], v[18:19], v[50:51] op_sel_hi:[1, 0]
	v_pk_mul_f32 v[10:11], v[16:17], v[50:51] op_sel_hi:[1, 0]
	s_nop 1
	v_pk_mul_f32 v[2:3], v[106:107], v[8:9]
	v_pk_mul_f32 v[0:1], v[104:105], v[10:11]
	global_store_dwordx4 v[28:29], v[0:3], off offset:1024
	global_load_dwordx4 v[34:37], v[52:53], off
	global_load_dwordx4 v[38:41], v[52:53], off offset:1024
	global_load_dwordx4 v[42:45], v[52:53], off offset:3072
	global_load_dwordx4 v[46:49], v[52:53], off offset:2048
	global_load_dwordx4 v[20:23], v[26:27], off
	global_load_dwordx4 v[16:19], v[26:27], off offset:1024
	global_load_dwordx4 v[0:3], v[26:27], off offset:3072
	global_load_dwordx4 v[8:11], v[26:27], off offset:2048
	s_waitcnt vmcnt(6)
	v_pk_mul_f32 v[54:55], v[40:41], v[40:41]
	v_pk_mul_f32 v[12:13], v[108:109], v[12:13]
	v_pk_mul_f32 v[14:15], v[110:111], v[14:15]
	global_store_dwordx4 v[28:29], v[12:15], off offset:2048
	s_waitcnt vmcnt(6)
	v_mul_f32_e32 v51, v44, v44
	v_pk_mul_f32 v[6:7], v[6:7], v[50:51] op_sel_hi:[1, 0]
	v_pk_mul_f32 v[4:5], v[4:5], v[50:51] op_sel_hi:[1, 0]
	v_pk_mul_f32 v[30:31], v[36:37], v[36:37]
	v_pk_mul_f32 v[32:33], v[34:35], v[34:35]
	v_pk_mul_f32 v[56:57], v[38:39], v[38:39]
	s_waitcnt vmcnt(5)
	v_mul_f32_e32 v58, v47, v47
	v_mul_f32_e32 v60, v49, v49
	s_waitcnt vmcnt(4)
	v_pk_mul_f32 v[62:63], v[22:23], v[22:23]
	v_pk_mul_f32 v[64:65], v[20:21], v[20:21]
	s_waitcnt vmcnt(3)
	v_pk_mul_f32 v[66:67], v[18:19], v[18:19]
	v_pk_mul_f32 v[68:69], v[16:17], v[16:17]
	v_pk_mov_b32 v[74:75], v[32:33], v[30:31] op_sel:[1, 0]
	v_mov_b32_e32 v33, v31
	v_pk_mov_b32 v[30:31], v[56:57], v[54:55] op_sel:[1, 0]
	v_mov_b32_e32 v57, v55
	v_pk_fma_f32 v[54:55], v[46:47], v[46:47], v[58:59] op_sel_hi:[1, 1, 0]
	v_pk_fma_f32 v[58:59], v[48:49], v[48:49], v[60:61] op_sel_hi:[1, 1, 0]
	v_pk_mov_b32 v[60:61], v[64:65], v[62:63] op_sel:[1, 0]
	v_mov_b32_e32 v65, v63
	v_pk_mov_b32 v[62:63], v[68:69], v[66:67] op_sel:[1, 0]
	v_mov_b32_e32 v69, v67
	v_mul_f32_e32 v73, v42, v42
	s_waitcnt vmcnt(1)
	v_mul_f32_e32 v70, v9, v9
	v_mul_f32_e32 v72, v11, v11
	v_pk_add_f32 v[32:33], v[74:75], v[32:33]
	v_mul_f32_e32 v76, v43, v43
	v_mul_f32_e32 v77, v45, v45
	v_mul_f32_e32 v78, v0, v0
	v_mul_f32_e32 v79, v1, v1
	v_mul_f32_e32 v80, v2, v2
	v_mul_f32_e32 v81, v3, v3
	v_pk_fma_f32 v[66:67], v[8:9], v[8:9], v[70:71] op_sel_hi:[1, 1, 0]
	v_pk_fma_f32 v[70:71], v[10:11], v[10:11], v[72:73] op_sel_hi:[1, 1, 0]
	v_mov_b32_e32 v55, v51
	v_mov_b32_e32 v59, v77
	v_mov_b32_e32 v67, v80
	v_mov_b32_e32 v71, v81
	v_pk_add_f32 v[50:51], v[66:67], v[70:71]
	v_pk_mul_f32 v[4:5], v[112:113], v[4:5]
	v_pk_mul_f32 v[6:7], v[114:115], v[6:7]
	global_store_dwordx4 v[28:29], v[4:7], off offset:3072
	v_pk_add_f32 v[12:13], v[30:31], v[56:57]
	v_pk_add_f32 v[14:15], v[60:61], v[64:65]
	v_pk_add_f32 v[28:29], v[62:63], v[68:69]
	v_pk_add_f32 v[30:31], v[32:33], v[32:33] op_sel:[0, 1] op_sel_hi:[1, 0]
	v_pk_add_f32 v[12:13], v[12:13], v[12:13] op_sel:[0, 1] op_sel_hi:[1, 0]
	v_pk_add_f32 v[14:15], v[14:15], v[14:15] op_sel:[0, 1] op_sel_hi:[1, 0]
	v_pk_add_f32 v[28:29], v[28:29], v[28:29] op_sel:[0, 1] op_sel_hi:[1, 0]
	v_mov_b32_e32 v31, v73
	v_mov_b32_e32 v13, v76
	v_mov_b32_e32 v15, v78
	v_mov_b32_e32 v29, v79
	v_pk_add_f32 v[32:33], v[54:55], v[58:59]
	v_pk_add_f32 v[12:13], v[30:31], v[12:13]
	v_pk_add_f32 v[14:15], v[14:15], v[28:29]
	v_pk_add_f32 v[12:13], v[12:13], v[32:33]
	v_pk_add_f32 v[14:15], v[14:15], v[50:51]
	v_mov_b32_e32 v29, v12
	v_mov_b32_e32 v28, v14
	v_mov_b32_e32 v12, v15
	v_pk_add_f32 v[12:13], v[28:29], v[12:13]
	s_waitcnt lgkmcnt(0)
	s_nop 1
	v_add_f32_dpp v12, v12, v12 quad_perm:[1, 0, 3, 2] row_mask:0xf bank_mask:0xf
	v_add_f32_dpp v13, v13, v13 quad_perm:[1, 0, 3, 2] row_mask:0xf bank_mask:0xf
	s_waitcnt lgkmcnt(0)
	s_nop 1
	v_add_f32_dpp v12, v12, v12 quad_perm:[2, 3, 0, 1] row_mask:0xf bank_mask:0xf
	v_add_f32_dpp v13, v13, v13 quad_perm:[2, 3, 0, 1] row_mask:0xf bank_mask:0xf
	s_waitcnt lgkmcnt(0)
	s_nop 1
	v_add_f32_dpp v12, v12, v12 row_half_mirror row_mask:0xf bank_mask:0xf
	v_add_f32_dpp v13, v13, v13 row_half_mirror row_mask:0xf bank_mask:0xf
	s_waitcnt lgkmcnt(0)
	s_nop 1
	v_add_f32_dpp v12, v12, v12 row_mirror row_mask:0xf bank_mask:0xf
	v_add_f32_dpp v13, v13, v13 row_mirror row_mask:0xf bank_mask:0xf
	ds_bpermute_b32 v15, v175, v13
	ds_bpermute_b32 v14, v175, v12
	s_waitcnt lgkmcnt(0)
	v_pk_add_f32 v[12:13], v[12:13], v[14:15]
	s_waitcnt lgkmcnt(0)
	v_mov_b32_e32 v14, v12
	v_mov_b32_e32 v15, v13
	s_nop 1
	v_permlane32_swap_b32_e32 v14, v12
	v_permlane32_swap_b32_e32 v15, v13
	v_pk_add_f32 v[12:13], v[12:13], v[14:15]
	s_nop 0
	v_pk_fma_f32 v[12:13], v[12:13], s[24:25], v[24:25] op_sel_hi:[1, 0, 0]
	s_nop 0
	v_mul_f32_e32 v14, 0x4b800000, v13
	v_cmp_gt_f32_e32 vcc, s57, v13
	s_nop 1
	v_cndmask_b32_e32 v13, v13, v14, vcc
	v_rsq_f32_e32 v13, v13
	s_nop 0
	v_mul_f32_e32 v14, 0x45800000, v13
	v_cndmask_b32_e32 v14, v13, v14, vcc
	v_pk_mul_f32 v[24:25], v[36:37], v[14:15] op_sel_hi:[1, 0]
	v_pk_mul_f32 v[28:29], v[34:35], v[14:15] op_sel_hi:[1, 0]
	v_mul_f32_e32 v13, 0x4b800000, v12
	v_cmp_gt_f32_e32 vcc, s57, v12
	v_pk_mul_f32 v[4:5], v[100:101], v[28:29]
	v_pk_mul_f32 v[6:7], v[102:103], v[24:25]
	global_store_dwordx4 v[52:53], v[4:7], off
	v_pk_mul_f32 v[24:25], v[40:41], v[14:15] op_sel_hi:[1, 0]
	v_pk_mul_f32 v[28:29], v[38:39], v[14:15] op_sel_hi:[1, 0]
	v_cndmask_b32_e32 v12, v12, v13, vcc
	v_rsq_f32_e32 v12, v12
	v_pk_mul_f32 v[4:5], v[104:105], v[28:29]
	v_pk_mul_f32 v[6:7], v[106:107], v[24:25]
	global_store_dwordx4 v[52:53], v[4:7], off offset:1024
	v_pk_mul_f32 v[24:25], v[48:49], v[14:15] op_sel_hi:[1, 0]
	v_pk_mul_f32 v[28:29], v[46:47], v[14:15] op_sel_hi:[1, 0]
	v_mul_f32_e32 v13, 0x45800000, v12
	v_cndmask_b32_e32 v12, v12, v13, vcc
	v_pk_mul_f32 v[20:21], v[20:21], v[12:13] op_sel_hi:[1, 0]
	v_pk_mul_f32 v[16:17], v[16:17], v[12:13] op_sel_hi:[1, 0]
	v_pk_mul_f32 v[10:11], v[10:11], v[12:13] op_sel_hi:[1, 0]
	v_pk_mul_f32 v[8:9], v[8:9], v[12:13] op_sel_hi:[1, 0]
	v_pk_mul_f32 v[2:3], v[2:3], v[12:13] op_sel_hi:[1, 0]
	v_pk_mul_f32 v[0:1], v[0:1], v[12:13] op_sel_hi:[1, 0]
	s_and_b64 vcc, exec, s[6:7]
	s_mov_b64 s[6:7], -1
	v_pk_mul_f32 v[4:5], v[108:109], v[28:29]
	v_pk_mul_f32 v[6:7], v[110:111], v[24:25]
	global_store_dwordx4 v[52:53], v[4:7], off offset:2048
	v_pk_mul_f32 v[24:25], v[44:45], v[14:15] op_sel_hi:[1, 0]
	v_pk_mul_f32 v[14:15], v[42:43], v[14:15] op_sel_hi:[1, 0]
	s_nop 1
	v_pk_mul_f32 v[6:7], v[114:115], v[24:25]
	v_pk_mul_f32 v[4:5], v[112:113], v[14:15]
	global_store_dwordx4 v[52:53], v[4:7], off offset:3072
	v_pk_mul_f32 v[14:15], v[22:23], v[12:13] op_sel_hi:[1, 0]
	s_nop 1
	v_pk_mul_f32 v[4:5], v[100:101], v[20:21]
	s_nop 1
	v_pk_mul_f32 v[6:7], v[102:103], v[14:15]
	global_store_dwordx4 v[26:27], v[4:7], off
	v_pk_mul_f32 v[14:15], v[18:19], v[12:13] op_sel_hi:[1, 0]
	s_nop 1
	v_pk_mul_f32 v[4:5], v[104:105], v[16:17]
	s_nop 1
	v_pk_mul_f32 v[6:7], v[106:107], v[14:15]
	global_store_dwordx4 v[26:27], v[4:7], off offset:1024
	s_nop 1
	v_pk_mul_f32 v[4:5], v[108:109], v[8:9]
	s_nop 1
	v_pk_mul_f32 v[6:7], v[110:111], v[10:11]
	global_store_dwordx4 v[26:27], v[4:7], off offset:2048
	v_pk_mul_f32 v[0:1], v[112:113], v[0:1]
	v_pk_mul_f32 v[2:3], v[114:115], v[2:3]
	global_store_dwordx4 v[26:27], v[0:3], off offset:3072
	s_cbranch_vccnz .LBB0_2507
	s_andn2_b64 vcc, exec, s[12:13]
	s_cbranch_vccnz .LBB0_2506
	s_barrier
	s_branch .LBB0_2506
